# v37 plus hand-written PEER pass epilogue: all four tokens' x1/gate/final_g loads in one batch instead of five dependent round trips per token
# speedup vs baseline: 1.0095x; 1.0053x over previous
; __device__ __forceinline__ void peer_tile(const Args& A, LAS unsigned char* lds, int tile) {
;     ...
;         for (int tk = 0; tk < 4; ++tk) {
;             const size_t m = (size_t)tile * 64 + tb + tk; const int b = (int)(m >> 11);
;             float* orow = A.out + m * 1024 + 16 * lane;
;             const float* g2 = MOD + b * 6144 + 5120 + 16 * lane;
;             f32x4 xv[4]; float ss = 0.f;
; #pragma unroll
;             for (int j = 0; j < 4; ++j) { const f32x4 x1 = *(const f32x4*)(orow + 4 * j), gg = *(const f32x4*)(g2 + 4 * j);
;                 const f32x4 pe = (f32x4){oacc[tk][2 * j][0], oacc[tk][2 * j][1], oacc[tk][2 * j + 1][0], oacc[tk][2 * j + 1][1]};
;                 xv[j] = x1 + gg * pe; ss += (xv[j][0] * xv[j][0] + xv[j][1] * xv[j][1]) + (xv[j][2] * xv[j][2] + xv[j][3] * xv[j][3]); }
.LBB0_798:
	v_mov_b32_e32 v129, v113
	s_waitcnt vmcnt(0)
	v_lshlrev_b64 v[0:1], 12, v[124:125]
	v_lshl_add_u64 v[2:3], v[130:131], 0, v[128:129]
	v_lshl_add_u64 v[0:1], s[48:49], 0, v[0:1]
	v_lshl_add_u64 v[2:3], v[2:3], 0, s[22:23]
	v_lshl_add_u64 v[48:49], v[0:1], 0, v[128:129]
	v_lshl_add_u64 v[50:51], v[48:49], 0, s[24:25]
	v_lshl_add_u64 v[52:53], v[48:49], 0, s[26:27]
	v_lshl_add_u64 v[54:55], v[48:49], 0, s[14:15]
	global_load_dwordx4 v[132:135], v[48:49], off
	global_load_dwordx4 v[136:139], v[48:49], off offset:16
	global_load_dwordx4 v[140:143], v[48:49], off offset:32
	global_load_dwordx4 v[144:147], v[48:49], off offset:48
	global_load_dwordx4 v[16:19], v[2:3], off
	global_load_dwordx4 v[20:23], v[2:3], off offset:16
	global_load_dwordx4 v[24:27], v[2:3], off offset:32
	global_load_dwordx4 v[28:31], v[2:3], off offset:48
	global_load_dwordx4 v[148:151], v[50:51], off
	global_load_dwordx4 v[152:155], v[50:51], off offset:16
	global_load_dwordx4 v[156:159], v[50:51], off offset:32
	global_load_dwordx4 v[160:163], v[50:51], off offset:48
	global_load_dwordx4 v[164:167], v[52:53], off
	global_load_dwordx4 v[168:171], v[52:53], off offset:16
	global_load_dwordx4 v[172:175], v[52:53], off offset:32
	global_load_dwordx4 v[176:179], v[52:53], off offset:48
	global_load_dwordx4 v[180:183], v[54:55], off
	global_load_dwordx4 v[184:187], v[54:55], off offset:16
	global_load_dwordx4 v[188:191], v[54:55], off offset:32
	global_load_dwordx4 v[192:195], v[54:55], off offset:48
	global_load_dwordx4 v[32:35], v[122:123], off
	global_load_dwordx4 v[36:39], v[122:123], off offset:16
	global_load_dwordx4 v[40:43], v[122:123], off offset:32
	global_load_dwordx4 v[44:47], v[122:123], off offset:48
	s_mov_b32 s3, 4
	s_mov_b64 s[4:5], 0
	s_waitcnt vmcnt(16)
	v_pk_fma_f32 v[132:133], v[208:209], v[16:17], v[132:133]
	v_pk_fma_f32 v[134:135], v[210:211], v[18:19], v[134:135]
	v_pk_fma_f32 v[136:137], v[204:205], v[20:21], v[136:137]
	v_pk_fma_f32 v[138:139], v[206:207], v[22:23], v[138:139]
	v_pk_fma_f32 v[140:141], v[200:201], v[24:25], v[140:141]
	v_pk_fma_f32 v[142:143], v[202:203], v[26:27], v[142:143]
	v_pk_fma_f32 v[144:145], v[196:197], v[28:29], v[144:145]
	v_pk_fma_f32 v[146:147], v[198:199], v[30:31], v[146:147]
	v_pk_mul_f32 v[0:1], v[132:133], v[132:133]
	v_pk_mul_f32 v[2:3], v[134:135], v[134:135]
	v_pk_mul_f32 v[4:5], v[136:137], v[136:137]
	v_pk_mul_f32 v[6:7], v[138:139], v[138:139]
	v_pk_mul_f32 v[8:9], v[140:141], v[140:141]
	v_pk_mul_f32 v[10:11], v[142:143], v[142:143]
	v_pk_mul_f32 v[12:13], v[144:145], v[144:145]
	v_pk_mul_f32 v[14:15], v[146:147], v[146:147]
	v_pk_add_f32 v[0:1], v[0:1], v[2:3]
	v_pk_add_f32 v[4:5], v[4:5], v[6:7]
	v_pk_add_f32 v[8:9], v[8:9], v[10:11]
	v_pk_add_f32 v[12:13], v[12:13], v[14:15]
	v_pk_add_f32 v[0:1], v[0:1], v[4:5]
	v_pk_add_f32 v[8:9], v[8:9], v[12:13]
	v_pk_add_f32 v[0:1], v[0:1], v[8:9]
	s_nop 0
	v_add_f32_e32 v56, v0, v1
	s_waitcnt vmcnt(12)
	v_pk_fma_f32 v[148:149], v[108:109], v[16:17], v[148:149]
	v_pk_fma_f32 v[150:151], v[110:111], v[18:19], v[150:151]
	v_pk_fma_f32 v[152:153], v[104:105], v[20:21], v[152:153]
	v_pk_fma_f32 v[154:155], v[106:107], v[22:23], v[154:155]
	v_pk_fma_f32 v[156:157], v[100:101], v[24:25], v[156:157]
	v_pk_fma_f32 v[158:159], v[102:103], v[26:27], v[158:159]
	v_pk_fma_f32 v[160:161], v[96:97], v[28:29], v[160:161]
	v_pk_fma_f32 v[162:163], v[98:99], v[30:31], v[162:163]
	v_pk_mul_f32 v[0:1], v[148:149], v[148:149]
	v_pk_mul_f32 v[2:3], v[150:151], v[150:151]
	v_pk_mul_f32 v[4:5], v[152:153], v[152:153]
	v_pk_mul_f32 v[6:7], v[154:155], v[154:155]
	v_pk_mul_f32 v[8:9], v[156:157], v[156:157]
	v_pk_mul_f32 v[10:11], v[158:159], v[158:159]
	v_pk_mul_f32 v[12:13], v[160:161], v[160:161]
	v_pk_mul_f32 v[14:15], v[162:163], v[162:163]
	v_pk_add_f32 v[0:1], v[0:1], v[2:3]
	v_pk_add_f32 v[4:5], v[4:5], v[6:7]
	v_pk_add_f32 v[8:9], v[8:9], v[10:11]
	v_pk_add_f32 v[12:13], v[12:13], v[14:15]
	v_pk_add_f32 v[0:1], v[0:1], v[4:5]
	v_pk_add_f32 v[8:9], v[8:9], v[12:13]
	v_pk_add_f32 v[0:1], v[0:1], v[8:9]
	s_nop 0
	v_add_f32_e32 v58, v0, v1
	s_waitcnt vmcnt(8)
	v_pk_fma_f32 v[164:165], v[92:93], v[16:17], v[164:165]
	v_pk_fma_f32 v[166:167], v[94:95], v[18:19], v[166:167]
	v_pk_fma_f32 v[168:169], v[88:89], v[20:21], v[168:169]
	v_pk_fma_f32 v[170:171], v[90:91], v[22:23], v[170:171]
	v_pk_fma_f32 v[172:173], v[84:85], v[24:25], v[172:173]
	v_pk_fma_f32 v[174:175], v[86:87], v[26:27], v[174:175]
	v_pk_fma_f32 v[176:177], v[80:81], v[28:29], v[176:177]
	v_pk_fma_f32 v[178:179], v[82:83], v[30:31], v[178:179]
	v_pk_mul_f32 v[0:1], v[164:165], v[164:165]
	v_pk_mul_f32 v[2:3], v[166:167], v[166:167]
	v_pk_mul_f32 v[4:5], v[168:169], v[168:169]
	v_pk_mul_f32 v[6:7], v[170:171], v[170:171]
	v_pk_mul_f32 v[8:9], v[172:173], v[172:173]
	v_pk_mul_f32 v[10:11], v[174:175], v[174:175]
	v_pk_mul_f32 v[12:13], v[176:177], v[176:177]
	v_pk_mul_f32 v[14:15], v[178:179], v[178:179]
	v_pk_add_f32 v[0:1], v[0:1], v[2:3]
	v_pk_add_f32 v[4:5], v[4:5], v[6:7]
	v_pk_add_f32 v[8:9], v[8:9], v[10:11]
	v_pk_add_f32 v[12:13], v[12:13], v[14:15]
	v_pk_add_f32 v[0:1], v[0:1], v[4:5]
	v_pk_add_f32 v[8:9], v[8:9], v[12:13]
	v_pk_add_f32 v[0:1], v[0:1], v[8:9]
	s_nop 0
	v_add_f32_e32 v60, v0, v1
	s_waitcnt vmcnt(4)
; __device__ __forceinline__ float wave_sum(float v) {
;     { const auto r = __builtin_amdgcn_permlane32_swap(__float_as_uint(v), __float_as_uint(v), false, false); v = __uint_as_float(r[0]) + __uint_as_float(r[1]); }
;     { const auto r = __builtin_amdgcn_permlane16_swap(__float_as_uint(v), __float_as_uint(v), false, false); v = __uint_as_float(r[0]) + __uint_as_float(r[1]); }
;     v += __int_as_float(__builtin_amdgcn_mov_dpp(__float_as_int(v), 0xB1, 0xF, 0xF, true));
;     v += __int_as_float(__builtin_amdgcn_mov_dpp(__float_as_int(v), 0x4E, 0xF, 0xF, true));
;     v += __int_as_float(__builtin_amdgcn_mov_dpp(__float_as_int(v), 0x141, 0xF, 0xF, true));
;     v += __int_as_float(__builtin_amdgcn_mov_dpp(__float_as_int(v), 0x140, 0xF, 0xF, true));
;     return v;
; __device__ __forceinline__ void peer_tile(const Args& A, LAS unsigned char* lds, int tile) {
;     ...
;                 xv[j] = x1 + gg * pe; ss += (xv[j][0] * xv[j][0] + xv[j][1] * xv[j][1]) + (xv[j][2] * xv[j][2] + xv[j][3] * xv[j][3]); }
;             const float rstd = rsqrtf(wave_sum(ss) * (1.f / 1024.f) + 1e-6f);
	v_pk_fma_f32 v[180:181], v[76:77], v[16:17], v[180:181]
	v_pk_fma_f32 v[182:183], v[78:79], v[18:19], v[182:183]
	v_pk_fma_f32 v[184:185], v[72:73], v[20:21], v[184:185]
	v_pk_fma_f32 v[186:187], v[74:75], v[22:23], v[186:187]
	v_pk_fma_f32 v[188:189], v[68:69], v[24:25], v[188:189]
	v_pk_fma_f32 v[190:191], v[70:71], v[26:27], v[190:191]
	v_pk_fma_f32 v[192:193], v[64:65], v[28:29], v[192:193]
	v_pk_fma_f32 v[194:195], v[66:67], v[30:31], v[194:195]
	v_pk_mul_f32 v[0:1], v[180:181], v[180:181]
	v_pk_mul_f32 v[2:3], v[182:183], v[182:183]
	v_pk_mul_f32 v[4:5], v[184:185], v[184:185]
	v_pk_mul_f32 v[6:7], v[186:187], v[186:187]
	v_pk_mul_f32 v[8:9], v[188:189], v[188:189]
	v_pk_mul_f32 v[10:11], v[190:191], v[190:191]
	v_pk_mul_f32 v[12:13], v[192:193], v[192:193]
	v_pk_mul_f32 v[14:15], v[194:195], v[194:195]
	v_pk_add_f32 v[0:1], v[0:1], v[2:3]
	v_pk_add_f32 v[4:5], v[4:5], v[6:7]
	v_pk_add_f32 v[8:9], v[8:9], v[10:11]
	v_pk_add_f32 v[12:13], v[12:13], v[14:15]
	v_pk_add_f32 v[0:1], v[0:1], v[4:5]
	v_pk_add_f32 v[8:9], v[8:9], v[12:13]
	v_pk_add_f32 v[0:1], v[0:1], v[8:9]
	s_nop 0
	v_add_f32_e32 v62, v0, v1
	v_mov_b32_e32 v57, v56
	v_mov_b32_e32 v59, v58
	v_mov_b32_e32 v61, v60
	v_mov_b32_e32 v63, v62
	v_permlane32_swap_b32_e32 v56, v57
	v_permlane32_swap_b32_e32 v58, v59
	v_permlane32_swap_b32_e32 v60, v61
	v_permlane32_swap_b32_e32 v62, v63
	v_add_f32_e32 v56, v56, v57
	v_add_f32_e32 v58, v58, v59
	v_add_f32_e32 v60, v60, v61
	v_add_f32_e32 v62, v62, v63
	v_mov_b32_e32 v57, v56
	v_mov_b32_e32 v59, v58
	v_mov_b32_e32 v61, v60
	v_mov_b32_e32 v63, v62
	v_permlane16_swap_b32_e32 v56, v57
	v_permlane16_swap_b32_e32 v58, v59
	v_permlane16_swap_b32_e32 v60, v61
	v_permlane16_swap_b32_e32 v62, v63
	v_add_f32_e32 v56, v56, v57
	v_add_f32_e32 v58, v58, v59
	v_add_f32_e32 v60, v60, v61
	v_add_f32_e32 v62, v62, v63
	v_add_f32_dpp v56, v56, v56 quad_perm:[1,0,3,2] row_mask:0xf bank_mask:0xf bound_ctrl:1
	v_add_f32_dpp v58, v58, v58 quad_perm:[1,0,3,2] row_mask:0xf bank_mask:0xf bound_ctrl:1
	v_add_f32_dpp v60, v60, v60 quad_perm:[1,0,3,2] row_mask:0xf bank_mask:0xf bound_ctrl:1
	v_add_f32_dpp v62, v62, v62 quad_perm:[1,0,3,2] row_mask:0xf bank_mask:0xf bound_ctrl:1
	v_add_f32_dpp v56, v56, v56 quad_perm:[2,3,0,1] row_mask:0xf bank_mask:0xf bound_ctrl:1
	v_add_f32_dpp v58, v58, v58 quad_perm:[2,3,0,1] row_mask:0xf bank_mask:0xf bound_ctrl:1
	v_add_f32_dpp v60, v60, v60 quad_perm:[2,3,0,1] row_mask:0xf bank_mask:0xf bound_ctrl:1
	v_add_f32_dpp v62, v62, v62 quad_perm:[2,3,0,1] row_mask:0xf bank_mask:0xf bound_ctrl:1
	v_add_f32_dpp v56, v56, v56 row_half_mirror row_mask:0xf bank_mask:0xf bound_ctrl:1
	v_add_f32_dpp v58, v58, v58 row_half_mirror row_mask:0xf bank_mask:0xf bound_ctrl:1
	v_add_f32_dpp v60, v60, v60 row_half_mirror row_mask:0xf bank_mask:0xf bound_ctrl:1
	v_add_f32_dpp v62, v62, v62 row_half_mirror row_mask:0xf bank_mask:0xf bound_ctrl:1
	v_add_f32_dpp v56, v56, v56 row_mirror row_mask:0xf bank_mask:0xf bound_ctrl:1
	v_add_f32_dpp v58, v58, v58 row_mirror row_mask:0xf bank_mask:0xf bound_ctrl:1
	v_add_f32_dpp v60, v60, v60 row_mirror row_mask:0xf bank_mask:0xf bound_ctrl:1
	v_add_f32_dpp v62, v62, v62 row_mirror row_mask:0xf bank_mask:0xf bound_ctrl:1
	v_fmamk_f32 v56, v56, 0x3a800000, v220
	v_fmamk_f32 v58, v58, 0x3a800000, v220
	v_fmamk_f32 v60, v60, 0x3a800000, v220
	v_fmamk_f32 v62, v62, 0x3a800000, v220
	v_rsq_f32_e32 v56, v56
	v_rsq_f32_e32 v58, v58
	v_rsq_f32_e32 v60, v60
	v_rsq_f32_e32 v62, v62
	s_waitcnt vmcnt(0)
; __device__ __forceinline__ void peer_tile(const Args& A, LAS unsigned char* lds, int tile) {
;     ...
; #pragma unroll
;             for (int j = 0; j < 4; ++j) { const f32x4 fg = *(const f32x4*)(A.final_g + 16 * lane + 4 * j); *(f32x4*)(orow + 4 * j) = xv[j] * rstd * fg; }
	v_pk_mul_f32 v[132:133], v[132:133], v[56:57] op_sel_hi:[1,0]
	v_pk_mul_f32 v[134:135], v[134:135], v[56:57] op_sel_hi:[1,0]
	v_pk_mul_f32 v[136:137], v[136:137], v[56:57] op_sel_hi:[1,0]
	v_pk_mul_f32 v[138:139], v[138:139], v[56:57] op_sel_hi:[1,0]
	v_pk_mul_f32 v[140:141], v[140:141], v[56:57] op_sel_hi:[1,0]
	v_pk_mul_f32 v[142:143], v[142:143], v[56:57] op_sel_hi:[1,0]
	v_pk_mul_f32 v[144:145], v[144:145], v[56:57] op_sel_hi:[1,0]
	v_pk_mul_f32 v[146:147], v[146:147], v[56:57] op_sel_hi:[1,0]
	v_pk_mul_f32 v[132:133], v[32:33], v[132:133]
	v_pk_mul_f32 v[134:135], v[34:35], v[134:135]
	v_pk_mul_f32 v[136:137], v[36:37], v[136:137]
	v_pk_mul_f32 v[138:139], v[38:39], v[138:139]
	v_pk_mul_f32 v[140:141], v[40:41], v[140:141]
	v_pk_mul_f32 v[142:143], v[42:43], v[142:143]
	v_pk_mul_f32 v[144:145], v[44:45], v[144:145]
	v_pk_mul_f32 v[146:147], v[46:47], v[146:147]
	global_store_dwordx4 v[48:49], v[132:135], off
	global_store_dwordx4 v[48:49], v[136:139], off offset:16
	global_store_dwordx4 v[48:49], v[140:143], off offset:32
	global_store_dwordx4 v[48:49], v[144:147], off offset:48
	v_pk_mul_f32 v[148:149], v[148:149], v[58:59] op_sel_hi:[1,0]
	v_pk_mul_f32 v[150:151], v[150:151], v[58:59] op_sel_hi:[1,0]
	v_pk_mul_f32 v[152:153], v[152:153], v[58:59] op_sel_hi:[1,0]
	v_pk_mul_f32 v[154:155], v[154:155], v[58:59] op_sel_hi:[1,0]
	v_pk_mul_f32 v[156:157], v[156:157], v[58:59] op_sel_hi:[1,0]
	v_pk_mul_f32 v[158:159], v[158:159], v[58:59] op_sel_hi:[1,0]
	v_pk_mul_f32 v[160:161], v[160:161], v[58:59] op_sel_hi:[1,0]
	v_pk_mul_f32 v[162:163], v[162:163], v[58:59] op_sel_hi:[1,0]
	v_pk_mul_f32 v[148:149], v[32:33], v[148:149]
	v_pk_mul_f32 v[150:151], v[34:35], v[150:151]
	v_pk_mul_f32 v[152:153], v[36:37], v[152:153]
	v_pk_mul_f32 v[154:155], v[38:39], v[154:155]
	v_pk_mul_f32 v[156:157], v[40:41], v[156:157]
	v_pk_mul_f32 v[158:159], v[42:43], v[158:159]
	v_pk_mul_f32 v[160:161], v[44:45], v[160:161]
	v_pk_mul_f32 v[162:163], v[46:47], v[162:163]
	global_store_dwordx4 v[50:51], v[148:151], off
	global_store_dwordx4 v[50:51], v[152:155], off offset:16
	global_store_dwordx4 v[50:51], v[156:159], off offset:32
	global_store_dwordx4 v[50:51], v[160:163], off offset:48
	v_pk_mul_f32 v[164:165], v[164:165], v[60:61] op_sel_hi:[1,0]
	v_pk_mul_f32 v[166:167], v[166:167], v[60:61] op_sel_hi:[1,0]
	v_pk_mul_f32 v[168:169], v[168:169], v[60:61] op_sel_hi:[1,0]
	v_pk_mul_f32 v[170:171], v[170:171], v[60:61] op_sel_hi:[1,0]
	v_pk_mul_f32 v[172:173], v[172:173], v[60:61] op_sel_hi:[1,0]
	v_pk_mul_f32 v[174:175], v[174:175], v[60:61] op_sel_hi:[1,0]
	v_pk_mul_f32 v[176:177], v[176:177], v[60:61] op_sel_hi:[1,0]
	v_pk_mul_f32 v[178:179], v[178:179], v[60:61] op_sel_hi:[1,0]
	v_pk_mul_f32 v[164:165], v[32:33], v[164:165]
	v_pk_mul_f32 v[166:167], v[34:35], v[166:167]
	v_pk_mul_f32 v[168:169], v[36:37], v[168:169]
	v_pk_mul_f32 v[170:171], v[38:39], v[170:171]
	v_pk_mul_f32 v[172:173], v[40:41], v[172:173]
	v_pk_mul_f32 v[174:175], v[42:43], v[174:175]
	v_pk_mul_f32 v[176:177], v[44:45], v[176:177]
	v_pk_mul_f32 v[178:179], v[46:47], v[178:179]
	global_store_dwordx4 v[52:53], v[164:167], off
	global_store_dwordx4 v[52:53], v[168:171], off offset:16
	global_store_dwordx4 v[52:53], v[172:175], off offset:32
	global_store_dwordx4 v[52:53], v[176:179], off offset:48
	v_pk_mul_f32 v[180:181], v[180:181], v[62:63] op_sel_hi:[1,0]
	v_pk_mul_f32 v[182:183], v[182:183], v[62:63] op_sel_hi:[1,0]
	v_pk_mul_f32 v[184:185], v[184:185], v[62:63] op_sel_hi:[1,0]
	v_pk_mul_f32 v[186:187], v[186:187], v[62:63] op_sel_hi:[1,0]
	v_pk_mul_f32 v[188:189], v[188:189], v[62:63] op_sel_hi:[1,0]
	v_pk_mul_f32 v[190:191], v[190:191], v[62:63] op_sel_hi:[1,0]
	v_pk_mul_f32 v[192:193], v[192:193], v[62:63] op_sel_hi:[1,0]
	v_pk_mul_f32 v[194:195], v[194:195], v[62:63] op_sel_hi:[1,0]
	v_pk_mul_f32 v[180:181], v[32:33], v[180:181]
	v_pk_mul_f32 v[182:183], v[34:35], v[182:183]
	v_pk_mul_f32 v[184:185], v[36:37], v[184:185]
	v_pk_mul_f32 v[186:187], v[38:39], v[186:187]
	v_pk_mul_f32 v[188:189], v[40:41], v[188:189]
	v_pk_mul_f32 v[190:191], v[42:43], v[190:191]
	v_pk_mul_f32 v[192:193], v[44:45], v[192:193]
	v_pk_mul_f32 v[194:195], v[46:47], v[194:195]
	global_store_dwordx4 v[54:55], v[180:183], off
	global_store_dwordx4 v[54:55], v[184:187], off offset:16
	global_store_dwordx4 v[54:55], v[188:191], off offset:32
	global_store_dwordx4 v[54:55], v[192:195], off offset:48
	s_and_b64 vcc, exec, s[0:1]
	s_cbranch_vccnz .LBB0_698
